# v57 with all hot loop heads pinned to 64-byte alignment (.p2align 6) to separate code-placement effects from the last three edits
# speedup vs baseline: 1.0056x; 1.0056x over previous
; #define PG8_STAGE(bufoff, gbase, voff) do { _Pragma("unroll") for (int _i = 0; _i < 2; ++_i) \
;         __builtin_amdgcn_global_load_lds((const unsigned*)((const char*)(gbase) + (voff)[_i]), (LAS unsigned*)(lds + (bufoff) + ldsw + _i * 8192), 16, 0, 0); } while (0)
; #define PG8_LDA(dst, b, h) do { _Pragma("unroll") for (int m = 0; m < 4; ++m) _Pragma("unroll") for (int k = 0; k < 2; ++k) dst[m][k] = *(const LAS h16x8*)(lds + PG8_SA(b, h) + aoff + m * 2048 + k * 1024); } while (0)
; #define PG8_LDB(dst, b, h) do { _Pragma("unroll") for (int n = 0; n < 2; ++n) _Pragma("unroll") for (int k = 0; k < 2; ++k) dst[n][k] = *(const LAS h16x8*)(lds + PG8_SB(b, h) + boff + n * 2048 + k * 1024); } while (0)
; #define PG8_WAIT_V(n) asm volatile("s_waitcnt vmcnt(" #n ")" ::: "memory")
; #define PG8_WAIT_L(n) asm volatile("s_waitcnt lgkmcnt(" #n ")" ::: "memory")
; template <class Epi>
; __device__ __forceinline__ void gemm_phase(LAS unsigned char* lds, const Gemm g, const StaticOrder& S, const Epi& E) {
;     ...
;         for (int t = 0; t < nt; t += 2) {
;             const bool last = (t == nt - 2);
;             const char* a1 = cA + (size_t)(t + 1) * kstep;
;             const char* a2 = last ? nA : cA + (size_t)(t + 2) * kstep; const char* b2 = last ? nB : cB + (size_t)(t + 2) * kstep;
;             const char* a3 = a2 + kstep; const char* b3 = b2 + kstep;
;             PG8_LDB(B0, 0, 0); PG8_LDB(B1, 0, 1); PG8_SCHED; PG8_LDA(At, 0, 0); PG8_STAGE(PG8_SA(1, 1), a1 + hstepA, voffA);
;             PG8_WAIT_V(8); PG8_WAIT_L(0); PG8_BAR; PG8_MMA(0, 0, At, B0); PG8_MMA(0, 1, At, B1); PG8_BAR; PG8_SCHED;
;             PG8_LDA(At, 0, 1); PG8_STAGE(PG8_SB(0, 0), b2, voffB); PG8_STAGE(PG8_SB(0, 1), b2 + hstepB, voffB); PG8_STAGE(PG8_SA(0, 0), a2, voffA);
;             PG8_WAIT_V(8); PG8_WAIT_L(0); PG8_BAR; PG8_MMA(1, 0, At, B0); PG8_MMA(1, 1, At, B1); PG8_BAR; PG8_SCHED;
;             PG8_LDB(B0, 1, 0); PG8_LDB(B1, 1, 1); PG8_SCHED; PG8_LDA(At, 1, 0); PG8_STAGE(PG8_SA(0, 1), a2 + hstepA, voffA);
;             PG8_WAIT_V(8); PG8_WAIT_L(0); PG8_BAR; PG8_MMA(0, 0, At, B0); PG8_MMA(0, 1, At, B1); PG8_BAR; PG8_SCHED;
;             PG8_LDA(At, 1, 1); PG8_STAGE(PG8_SB(1, 0), b3, voffB); PG8_STAGE(PG8_SB(1, 1), b3 + hstepB, voffB); PG8_STAGE(PG8_SA(1, 0), a3, voffA);
;             PG8_WAIT_V(8); PG8_WAIT_L(0); PG8_BAR; PG8_MMA(1, 0, At, B0); PG8_MMA(1, 1, At, B1); PG8_BAR; PG8_SCHED;
.Lprio_140:
	.p2align	6

; #define LDS_BARRIER() do { asm volatile("s_waitcnt lgkmcnt(0)" ::: "memory"); __builtin_amdgcn_s_barrier(); asm volatile("" ::: "memory"); } while (0)
; #define LAUNDER_V(x) asm volatile("" : "+v"(x))
; __device__ __forceinline__ void phase_scan(h16* Pdn, const h16* Tg, const h16* qkg, const float* gcg, const float* betag, const float* s2g, unsigned char* ldsb) {
;     ...
;     if (bid < 128) {
;         const int item = bid;
;         const int bh = (item & 7) * 8 + (item >> 4), s = (item >> 3) & 1, b = bh >> 3, h = bh & 7;
;         f32x4 S[8];
; #pragma unroll
;         for (int tk = 0; tk < 8; ++tk) S[tk] = (f32x4){0.f, 0.f, 0.f, 0.f};
;     ...
;         if (w >= 4) {
;             h16x8 R0[15], R1[15], R2[15];
;             SCAN_LD(0, R0); SCAN_ST(0, R0);
;             SCAN_LD(1, R1); SCAN_LD(2, R2); SCAN_LD(3, R0);
;             LDS_BARRIER();
; #pragma unroll 1
;             for (int n = 0; n < 63; n += 3) {
;                 SCAN_ST((n + 1) & 1, R1); if (n + 4 < 64) SCAN_LD(n + 4, R1);
;                 LDS_BARRIER();
;                 SCAN_ST((n + 2) & 1, R2); if (n + 5 < 64) SCAN_LD(n + 5, R2);
;                 LDS_BARRIER();
;                 SCAN_ST((n + 3) & 1, R0); if (n + 6 < 64) SCAN_LD(n + 6, R0);
;                 LDS_BARRIER();
;             }
;             LDS_BARRIER();
;         } else {
;         int tc = tid; LAUNDER_V(tc);
;         const int lane = tc & 63, fr = lane & 15, g = lane >> 4; (void)lane;
;         LDS_BARRIER();
; #pragma unroll 1
;         for (int n = 0; n < 64; ++n) {
.LBB0_243:
	s_and_b64 vcc, exec, s[0:1]
	s_cbranch_vccz .LBB0_283
	v_mov_b32_e32 v170, v192
	s_mov_b32 s0, s52
	s_cmpk_gt_i32 s0, 0x7f
	v_readfirstlane_b32 s1, v170
	s_cbranch_scc1 .LBB0_283
	s_ashr_i32 s6, s1, 6
	s_lshl_b32 s1, s0, 3
	s_and_b32 s4, s1, 56
	s_ashr_i32 s1, s0, 4
	s_add_i32 s4, s4, s1
	s_ashr_i32 s5, s4, 3
	s_bfe_u32 s3, s0, 0x10003
	s_and_b32 s8, s1, 7
	s_cmp_lt_i32 s6, 4
	s_mov_b64 s[0:1], -1
	s_cbranch_scc0 .LBB0_249
	v_mov_b32_e32 v0, v170
	s_lshl_b32 s6, s6, 4
	v_lshrrev_b32_e32 v3, 2, v0
	v_and_b32_e32 v1, 15, v0
	v_and_b32_e32 v171, 12, v3
	v_bfe_u32 v3, v0, 2, 4
	v_lshlrev_b32_e32 v0, 2, v0
	s_lshl_b32 s0, s5, 24
	s_lshl_b32 s1, s8, 7
	v_and_b32_e32 v4, 12, v0
	v_or_b32_e32 v0, s6, v1
	s_waitcnt lgkmcnt(0)
	s_barrier
	s_lshl_b32 s9, s3, 6
	v_lshl_add_u32 v138, v171, 12, v0
	s_or_b32 s0, s0, s1
	v_readlane_b32 s36, v254, 43
	v_mul_u32_u24_e32 v2, 0x88, v1
	v_add_u32_e32 v140, 0x1000, v138
	v_add_u32_e32 v142, 0x2000, v138
	v_add_u32_e32 v144, 0x3000, v138
	v_add_u32_e32 v146, 0x10000, v138
	v_add_u32_e32 v148, 0x11000, v138
	v_add_u32_e32 v150, 0x12000, v138
	v_add_u32_e32 v152, 0x13000, v138
	v_add_u32_e32 v154, 0x20000, v138
	v_add_u32_e32 v156, 0x21000, v138
	v_add_u32_e32 v158, 0x22000, v138
	v_add_u32_e32 v160, 0x23000, v138
	v_add_u32_e32 v162, 0x30000, v138
	v_add_u32_e32 v164, 0x31000, v138
	v_add_u32_e32 v166, 0x32000, v138
	v_add_u32_e32 v168, 0x33000, v138
	v_lshlrev_b32_e32 v175, 1, v171
	s_or_b32 s0, s0, s9
	v_readlane_b32 s45, v254, 52
	v_mov_b32_e32 v0, 0
	v_lshlrev_b32_e32 v172, 7, v3
	v_mul_u32_u24_e32 v173, 0x90, v1
	v_mul_u32_u24_e32 v174, 0x110, v3
	v_ashrrev_i32_e32 v139, 31, v138
	v_ashrrev_i32_e32 v141, 31, v140
	v_ashrrev_i32_e32 v143, 31, v142
	v_ashrrev_i32_e32 v145, 31, v144
	v_ashrrev_i32_e32 v147, 31, v146
	v_ashrrev_i32_e32 v149, 31, v148
	v_ashrrev_i32_e32 v151, 31, v150
	v_ashrrev_i32_e32 v153, 31, v152
	v_ashrrev_i32_e32 v155, 31, v154
	v_ashrrev_i32_e32 v157, 31, v156
	v_ashrrev_i32_e32 v159, 31, v158
	v_ashrrev_i32_e32 v161, 31, v160
	v_ashrrev_i32_e32 v163, 31, v162
	v_ashrrev_i32_e32 v165, 31, v164
	v_ashrrev_i32_e32 v167, 31, v166
	v_ashrrev_i32_e32 v169, 31, v168
	s_mov_b32 s7, 0
	v_sub_u32_e32 v176, 0, v175
	s_mov_b32 s13, s45
	s_or_b32 s12, s0, 0x800
	v_lshlrev_b32_e32 v177, 1, v2
	v_lshlrev_b32_e32 v178, 1, v4
	v_mov_b32_e32 v1, v0
	v_mov_b32_e32 v2, v0
	v_mov_b32_e32 v3, v0
	v_mov_b32_e32 v4, v0
	v_mov_b32_e32 v5, v0
	v_mov_b32_e32 v6, v0
	v_mov_b32_e32 v7, v0
	v_mov_b32_e32 v8, v0
	v_mov_b32_e32 v9, v0
	v_mov_b32_e32 v10, v0
	v_mov_b32_e32 v11, v0
	v_mov_b32_e32 v12, v0
	v_mov_b32_e32 v13, v0
	v_mov_b32_e32 v14, v0
	v_mov_b32_e32 v15, v0
	v_mov_b32_e32 v16, v0
	v_mov_b32_e32 v17, v0
	v_mov_b32_e32 v18, v0
	v_mov_b32_e32 v19, v0
	v_mov_b32_e32 v20, v0
	v_mov_b32_e32 v21, v0
	v_mov_b32_e32 v22, v0
	v_mov_b32_e32 v23, v0
	v_mov_b32_e32 v24, v0
	v_mov_b32_e32 v25, v0
	v_mov_b32_e32 v26, v0
	v_mov_b32_e32 v27, v0
	v_mov_b32_e32 v28, v0
	v_mov_b32_e32 v29, v0
	v_mov_b32_e32 v30, v0
	v_mov_b32_e32 v31, v0
	v_readlane_b32 s37, v254, 44
	v_readlane_b32 s38, v254, 45
	v_readlane_b32 s39, v254, 46
	v_readlane_b32 s40, v254, 47
	v_readlane_b32 s41, v254, 48
	v_readlane_b32 s42, v254, 49
	v_readlane_b32 s43, v254, 50
	v_readlane_b32 s44, v254, 51
	v_readlane_b32 s46, v254, 53
	v_readlane_b32 s47, v254, 54
	v_readlane_b32 s48, v254, 55
	v_readlane_b32 s49, v254, 56
	v_readlane_b32 s50, v254, 57
	v_readlane_b32 s51, v254, 58
	s_setprio 2
	.p2align	6

; #define LDS_BARRIER() do { asm volatile("s_waitcnt lgkmcnt(0)" ::: "memory"); __builtin_amdgcn_s_barrier(); asm volatile("" ::: "memory"); } while (0)
; __device__ __forceinline__ void phase_dnprep(h16* Pdn, const h16* halo, const float* bd, const float* convw, const float* a_log, const float* dt_bias,
;                              h16* Tg, h16* qkg, float* gcg, float* betag, float* s2g, LAS unsigned char* ldsl, unsigned char* ldsb) {
;     ...
;         {
;             const int which = tl >> 8, r = (tl >> 4) & 15, c = tl & 15, rb = which ? 48 : 16, cb = which ? 32 : 0;
;             float sacc = 0.f;
; #pragma unroll
;             for (int k = 0; k < 16; ++k) sacc += Mm[(rb + r) * 68 + cb + k] * X[(cb + k) * 68 + cb + c];
;             Zs[(which * 16 + r) * 17 + c] = sacc;
;         }
;         LDS_BARRIER();
;         {
;             const int which = tl >> 8, r = (tl >> 4) & 15, c = tl & 15, rb = which ? 48 : 16, cb = which ? 32 : 0;
;             float sacc = 0.f;
; #pragma unroll
;             for (int m = 0; m < 16; ++m) sacc += X[(rb + r) * 68 + rb + m] * Zs[(which * 16 + m) * 17 + c];
;             X[(rb + r) * 68 + cb + c] = -sacc;
;         }
;         LDS_BARRIER();
;         {
;             float zv[2];
; #pragma unroll
;             for (int it = 0; it < 2; ++it) {
;                 const int e = tl + 512 * it, r = e >> 5, c = e & 31;
;                 float sacc = 0.f;
; #pragma unroll
;                 for (int k = 0; k < 32; ++k) sacc += Mm[(32 + r) * 68 + k] * X[k * 68 + c];
;                 zv[it] = sacc;
;             }
.LBB0_320:
	s_or_b64 exec, exec, s[0:1]
	s_movk_i32 s0, 0x100
	v_cmp_gt_u32_e32 vcc, s0, v82
	v_bfe_u32 v0, v82, 4, 4
	v_lshlrev_b32_e32 v27, 2, v100
	v_cndmask_b32_e64 v22, 48, 16, vcc
	v_cndmask_b32_e64 v1, 32, 0, vcc
	v_or_b32_e32 v23, v22, v0
	v_mul_u32_u24_e32 v0, 0x110, v23
	v_lshlrev_b32_e32 v26, 2, v1
	v_add3_u32 v12, s3, v0, v26
	v_mul_u32_u24_e32 v0, 0x110, v1
	v_add_u32_e32 v16, s78, v27
	s_waitcnt lgkmcnt(0)
	s_barrier
	v_add3_u32 v24, v16, v26, v0
	ds_read2_b32 v[18:19], v24 offset1:68
	ds_read_b128 v[0:3], v12
	ds_read_b128 v[4:7], v12 offset:16
	ds_read2_b32 v[20:21], v24 offset0:136 offset1:204
	ds_read_b128 v[8:11], v12 offset:32
	ds_read_b128 v[12:15], v12 offset:48
	s_waitcnt lgkmcnt(4)
	v_fma_f32 v25, v0, v18, 0
	v_fmac_f32_e32 v25, v1, v19
	s_waitcnt lgkmcnt(2)
	v_fmac_f32_e32 v25, v2, v20
	v_add_u32_e32 v2, 0x400, v24
	ds_read2_b32 v[0:1], v2 offset0:16 offset1:84
	v_fmac_f32_e32 v25, v3, v21
	ds_read2_b32 v[2:3], v2 offset0:152 offset1:220
	v_add_u32_e32 v20, 0x800, v24
	ds_read2_b32 v[18:19], v20 offset0:32 offset1:100
	s_waitcnt lgkmcnt(2)
	v_fmac_f32_e32 v25, v4, v0
	v_fmac_f32_e32 v25, v5, v1
	ds_read2_b32 v[0:1], v20 offset0:168 offset1:236
	s_waitcnt lgkmcnt(2)
	v_fmac_f32_e32 v25, v6, v2
	v_add_u32_e32 v4, 0xc00, v24
	v_fmac_f32_e32 v25, v7, v3
	ds_read2_b32 v[2:3], v4 offset0:48 offset1:116
	s_waitcnt lgkmcnt(2)
	v_fmac_f32_e32 v25, v8, v18
	v_fmac_f32_e32 v25, v9, v19
	ds_read2_b32 v[4:5], v4 offset0:184 offset1:252
	s_waitcnt lgkmcnt(2)
	v_fmac_f32_e32 v25, v10, v0
	v_fmac_f32_e32 v25, v11, v1
	s_waitcnt lgkmcnt(1)
	v_fmac_f32_e32 v25, v12, v2
	v_lshrrev_b32_e32 v17, 4, v82
	v_fmac_f32_e32 v25, v13, v3
	v_ashrrev_i32_e32 v28, 4, v82
	s_waitcnt lgkmcnt(0)
	v_fmac_f32_e32 v25, v14, v4
	v_bfi_b32 v0, -16, v28, v17
	s_movk_i32 s5, 0x44
	v_fmac_f32_e32 v25, v15, v5
	v_mad_u64_u32 v[0:1], s[0:1], v0, s5, v[16:17]
	ds_write_b32 v0, v25 offset:17408
	v_mov_b32_e32 v0, s78
	s_movk_i32 s4, 0x110
	v_and_b32_e32 v2, -16, v28
	v_mad_u32_u24 v17, v23, s4, v0
	v_mad_u64_u32 v[18:19], s[0:1], v2, s5, v[16:17]
	s_waitcnt lgkmcnt(0)
	s_barrier
	v_lshl_add_u32 v12, v22, 2, v17
	v_add_u32_e32 v19, 0x4400, v18
	ds_read2_b32 v[20:21], v19 offset1:17
	ds_read_b128 v[0:3], v12
	ds_read_b128 v[4:7], v12 offset:16
	ds_read2_b32 v[22:23], v19 offset0:34 offset1:51
	ds_read_b128 v[8:11], v12 offset:32
	ds_read_b128 v[12:15], v12 offset:48
	ds_read2_b32 v[24:25], v19 offset0:68 offset1:85
	s_waitcnt lgkmcnt(5)
	v_fma_f32 v20, v0, v20, 0
	v_fmac_f32_e32 v20, v1, v21
	ds_read2_b32 v[0:1], v19 offset0:102 offset1:119
	s_waitcnt lgkmcnt(4)
	v_fmac_f32_e32 v20, v2, v22
	v_fmac_f32_e32 v20, v3, v23
	ds_read2_b32 v[2:3], v19 offset0:136 offset1:153
	s_waitcnt lgkmcnt(2)
	v_fmac_f32_e32 v20, v4, v24
	v_fmac_f32_e32 v20, v5, v25
	ds_read2_b32 v[4:5], v19 offset0:170 offset1:187
	s_waitcnt lgkmcnt(2)
	v_fmac_f32_e32 v20, v6, v0
	v_fmac_f32_e32 v20, v7, v1
	ds_read2_b32 v[0:1], v19 offset0:204 offset1:221
	s_waitcnt lgkmcnt(2)
	v_fmac_f32_e32 v20, v8, v2
	v_or_b32_e32 v2, 15, v28
	v_fmac_f32_e32 v20, v9, v3
	v_mad_u64_u32 v[2:3], s[0:1], v2, s5, v[16:17]
	s_waitcnt lgkmcnt(1)
	v_fmac_f32_e32 v20, v10, v4
	ds_read_b32 v3, v18 offset:18360
	ds_read_b32 v2, v2 offset:17408
	v_fmac_f32_e32 v20, v11, v5
	s_waitcnt lgkmcnt(2)
	v_fmac_f32_e32 v20, v12, v0
	v_fmac_f32_e32 v20, v13, v1
	s_waitcnt lgkmcnt(1)
	v_fmac_f32_e32 v20, v14, v3
	s_waitcnt lgkmcnt(0)
	v_fmac_f32_e32 v20, v15, v2
	v_xor_b32_e32 v0, 0x80000000, v20
	v_add3_u32 v1, v17, v26, v27
	ds_write_b32 v1, v0
	v_ashrrev_i32_e32 v1, 5, v82
	s_waitcnt lgkmcnt(0)
	s_barrier
	v_add_u32_e32 v0, s78, v98
	v_mul_lo_u32 v32, v1, s4
	v_add_u32_e32 v46, s3, v32
	ds_read2_b32 v[18:19], v0 offset1:68
	ds_read_b128 v[2:5], v46 offset:8704
	ds_read_b128 v[6:9], v46 offset:8720
	ds_read2_b32 v[20:21], v0 offset0:136 offset1:204
	ds_read_b128 v[10:13], v46 offset:8736
	ds_read_b128 v[14:17], v46 offset:8752
	s_waitcnt lgkmcnt(4)
	v_fma_f32 v52, v2, v18, 0
	v_add_u32_e32 v2, 0x400, v0
	ds_read2_b32 v[22:23], v2 offset0:16 offset1:84
	v_fmac_f32_e32 v52, v3, v19
	ds_read2_b32 v[24:25], v2 offset0:152 offset1:220
	s_waitcnt lgkmcnt(4)
	v_fmac_f32_e32 v52, v4, v20
	v_add_u32_e32 v2, 0x800, v0
	v_fmac_f32_e32 v52, v5, v21
	ds_read2_b32 v[26:27], v2 offset0:32 offset1:100
	s_waitcnt lgkmcnt(2)
	v_fmac_f32_e32 v52, v6, v22
	v_fmac_f32_e32 v52, v7, v23
	ds_read2_b32 v[28:29], v2 offset0:168 offset1:236
	s_waitcnt lgkmcnt(2)
	v_fmac_f32_e32 v52, v8, v24
	v_add_u32_e32 v2, 0xc00, v0
	v_fmac_f32_e32 v52, v9, v25
	ds_read2_b32 v[30:31], v2 offset0:48 offset1:116
	s_waitcnt lgkmcnt(2)
	v_fmac_f32_e32 v52, v10, v26
	v_fmac_f32_e32 v52, v11, v27
	ds_read2_b32 v[34:35], v2 offset0:184 offset1:252
	s_waitcnt lgkmcnt(2)
	v_fmac_f32_e32 v52, v12, v28
	v_add_u32_e32 v6, 0x1000, v0
	v_fmac_f32_e32 v52, v13, v29
	ds_read_b128 v[2:5], v46 offset:8768
	ds_read2_b32 v[36:37], v6 offset0:64 offset1:132
	s_waitcnt lgkmcnt(3)
	v_fmac_f32_e32 v52, v14, v30
	v_fmac_f32_e32 v52, v15, v31
	v_add_u32_e32 v6, 0x1200, v0
	s_waitcnt lgkmcnt(2)
	v_fmac_f32_e32 v52, v16, v34
	ds_read2_b32 v[38:39], v6 offset0:72 offset1:140
	ds_read_b128 v[6:9], v46 offset:8784
	v_add_u32_e32 v10, 0x1400, v0
	v_fmac_f32_e32 v52, v17, v35
	ds_read2_b32 v[40:41], v10 offset0:80 offset1:148
	s_waitcnt lgkmcnt(3)
	v_fmac_f32_e32 v52, v2, v36
	v_fmac_f32_e32 v52, v3, v37
	s_waitcnt lgkmcnt(2)
	v_fmac_f32_e32 v52, v4, v38
	v_fmac_f32_e32 v52, v5, v39
	v_add_u32_e32 v2, 0x1600, v0
	s_waitcnt lgkmcnt(0)
	v_fmac_f32_e32 v52, v6, v40
	ds_read2_b32 v[42:43], v2 offset0:88 offset1:156
	ds_read_b128 v[2:5], v46 offset:8800
	v_add_u32_e32 v6, 0x1800, v0
	ds_read2_b32 v[44:45], v6 offset0:96 offset1:164
	v_fmac_f32_e32 v52, v7, v41
	s_waitcnt lgkmcnt(2)
; __device__ __forceinline__ void phase_dnprep(h16* Pdn, const h16* halo, const float* bd, const float* convw, const float* a_log, const float* dt_bias,
;                              h16* Tg, h16* qkg, float* gcg, float* betag, float* s2g, LAS unsigned char* ldsl, unsigned char* ldsb) {
;     ...
;         {
;             float zv[2];
; #pragma unroll
;             for (int it = 0; it < 2; ++it) {
;                 const int e = tl + 512 * it, r = e >> 5, c = e & 31;
;                 float sacc = 0.f;
; #pragma unroll
;                 for (int k = 0; k < 32; ++k) sacc += Mm[(32 + r) * 68 + k] * X[k * 68 + c];
;                 zv[it] = sacc;
;             }
; #pragma unroll
;             for (int it = 0; it < 2; ++it) { const int e = tl + 512 * it, r = e >> 5, c = e & 31; Zs[r * 33 + c] = zv[it]; }
;         }
	v_fmac_f32_e32 v52, v8, v42
	v_fmac_f32_e32 v52, v9, v43
	ds_read_b128 v[6:9], v46 offset:8816
	s_waitcnt lgkmcnt(1)
	v_fmac_f32_e32 v52, v2, v44
	v_add_u32_e32 v2, 0x1a00, v0
	ds_read2_b32 v[46:47], v2 offset0:104 offset1:172
	v_add_u32_e32 v2, 0x1c00, v0
	ds_read2_b32 v[48:49], v2 offset0:112 offset1:180
	v_add_u32_e32 v2, 0x1e00, v0
	ds_read2_b32 v[50:51], v2 offset0:120 offset1:188
	v_add_u32_e32 v2, 0x200, v82
	v_ashrrev_i32_e32 v53, 5, v2
	v_fmac_f32_e32 v52, v3, v45
	v_mul_lo_u32 v54, v53, s4
	s_waitcnt lgkmcnt(2)
	v_fmac_f32_e32 v52, v4, v46
	v_add_u32_e32 v55, s3, v54
	v_fmac_f32_e32 v52, v5, v47
	ds_read_b128 v[2:5], v55 offset:8704
	s_waitcnt lgkmcnt(2)
	v_fmac_f32_e32 v52, v6, v48
	v_fmac_f32_e32 v52, v7, v49
	s_waitcnt lgkmcnt(1)
	v_fmac_f32_e32 v52, v8, v50
	v_fmac_f32_e32 v52, v9, v51
	s_waitcnt lgkmcnt(0)
	v_fma_f32 v18, v18, v2, 0
	ds_read_b128 v[6:9], v55 offset:8720
	ds_read_b128 v[10:13], v55 offset:8736
	ds_read_b128 v[14:17], v55 offset:8752
	v_fmac_f32_e32 v18, v19, v3
	v_fmac_f32_e32 v18, v20, v4
	v_fmac_f32_e32 v18, v21, v5
	s_waitcnt lgkmcnt(2)
	v_fmac_f32_e32 v18, v22, v6
	v_fmac_f32_e32 v18, v23, v7
	v_fmac_f32_e32 v18, v24, v8
	v_fmac_f32_e32 v18, v25, v9
	s_waitcnt lgkmcnt(1)
	v_fmac_f32_e32 v18, v26, v10
	v_fmac_f32_e32 v18, v27, v11
	v_fmac_f32_e32 v18, v28, v12
	v_fmac_f32_e32 v18, v29, v13
	ds_read_b128 v[2:5], v55 offset:8768
	ds_read_b128 v[6:9], v55 offset:8784
	s_waitcnt lgkmcnt(2)
	v_fmac_f32_e32 v18, v30, v14
	v_fmac_f32_e32 v18, v31, v15
	v_fmac_f32_e32 v18, v34, v16
	v_fmac_f32_e32 v18, v35, v17
	s_waitcnt lgkmcnt(1)
	v_fmac_f32_e32 v18, v36, v2
	v_fmac_f32_e32 v18, v37, v3
	v_fmac_f32_e32 v18, v38, v4
	v_fmac_f32_e32 v18, v39, v5
	ds_read_b128 v[2:5], v55 offset:8800
	s_waitcnt lgkmcnt(1)
	v_fmac_f32_e32 v18, v40, v6
	v_fmac_f32_e32 v18, v41, v7
	v_fmac_f32_e32 v18, v42, v8
	v_fmac_f32_e32 v18, v43, v9
	ds_read_b128 v[6:9], v55 offset:8816
	s_waitcnt lgkmcnt(1)
	v_fmac_f32_e32 v18, v44, v2
	v_fmac_f32_e32 v18, v45, v3
	v_fmac_f32_e32 v18, v46, v4
	v_fmac_f32_e32 v18, v47, v5
	s_waitcnt lgkmcnt(0)
	v_fmac_f32_e32 v18, v48, v6
	v_fmac_f32_e32 v18, v49, v7
	s_movk_i32 s3, 0x84
	v_fmac_f32_e32 v18, v50, v8
	v_mad_u64_u32 v[2:3], s[0:1], v1, s3, v[0:1]
	v_fmac_f32_e32 v18, v51, v9
	ds_write_b32 v2, v52 offset:17408
	v_mad_u64_u32 v[2:3], s[0:1], v53, s3, v[0:1]
	ds_write_b32 v2, v18 offset:17408
	s_waitcnt lgkmcnt(0)
	s_barrier
; #define LDS_BARRIER() do { asm volatile("s_waitcnt lgkmcnt(0)" ::: "memory"); __builtin_amdgcn_s_barrier(); asm volatile("" ::: "memory"); } while (0)
; __device__ __forceinline__ void phase_dnprep(h16* Pdn, const h16* halo, const float* bd, const float* convw, const float* a_log, const float* dt_bias,
;                              h16* Tg, h16* qkg, float* gcg, float* betag, float* s2g, LAS unsigned char* ldsl, unsigned char* ldsb) {
;     ...
; #pragma unroll
;         for (int it = 0; it < 2; ++it) {
;             const int e = tl + 512 * it, r = e >> 5, c = e & 31;
;             float sacc = 0.f;
; #pragma unroll
;             for (int m = 0; m < 32; ++m) sacc += X[(32 + r) * 68 + 32 + m] * Zs[m * 33 + c];
;             X[(32 + r) * 68 + c] = -sacc;
;         }
;         LDS_BARRIER();
;         {
;             const int i = tl >> 3, part = tl & 7;
;             h16x8 o;
; #pragma unroll
;             for (int e = 0; e < 8; ++e) o[e] = (h16)X[i * 68 + 8 * part + e];
;             gst((h16x8*)(Tg + (bh0 + i) * 64 + 8 * part), o);
;         }
;         LDS_BARRIER();
	v_add_u32_e32 v1, s78, v32
	ds_read_b128 v[2:5], v1 offset:8832
	ds_read_b128 v[6:9], v1 offset:8848
	ds_read_b32 v22, v0 offset:17408
	v_add_u32_e32 v23, 0x4400, v0
	ds_read2_b32 v[18:19], v23 offset0:33 offset1:66
	ds_read_b128 v[10:13], v1 offset:8864
	ds_read_b128 v[14:17], v1 offset:8880
	ds_read2_b32 v[20:21], v23 offset0:99 offset1:132
	ds_read_b32 v32, v0 offset:21500
	v_readlane_b32 s0, v255, 22
	v_readlane_b32 s1, v255, 23
	s_waitcnt lgkmcnt(5)
	v_fma_f32 v50, v2, v22, 0
	ds_read2_b32 v[22:23], v23 offset0:165 offset1:198
	s_waitcnt lgkmcnt(5)
	v_fmac_f32_e32 v50, v3, v18
	v_add_u32_e32 v2, 0x4600, v0
	v_fmac_f32_e32 v50, v4, v19
	ds_read2_b32 v[24:25], v2 offset0:103 offset1:136
	s_waitcnt lgkmcnt(3)
	v_fmac_f32_e32 v50, v5, v20
	v_add_u32_e32 v2, 0x4800, v0
	v_fmac_f32_e32 v50, v6, v21
	ds_read2_b32 v[26:27], v2 offset0:41 offset1:74
	s_waitcnt lgkmcnt(2)
	v_fmac_f32_e32 v50, v7, v22
	v_fmac_f32_e32 v50, v8, v23
	ds_read2_b32 v[28:29], v2 offset0:107 offset1:140
	s_waitcnt lgkmcnt(2)
	v_fmac_f32_e32 v50, v9, v24
	v_fmac_f32_e32 v50, v10, v25
	ds_read2_b32 v[30:31], v2 offset0:173 offset1:206
	s_waitcnt lgkmcnt(2)
	v_fmac_f32_e32 v50, v11, v26
	v_fmac_f32_e32 v50, v12, v27
	v_add_u32_e32 v2, 0x4a00, v0
	s_waitcnt lgkmcnt(1)
	v_fmac_f32_e32 v50, v13, v28
	ds_read2_b32 v[34:35], v2 offset0:111 offset1:144
	ds_read_b128 v[2:5], v1 offset:8896
	v_add_u32_e32 v10, 0x4c00, v0
	v_fmac_f32_e32 v50, v14, v29
	ds_read2_b32 v[36:37], v10 offset0:49 offset1:82
	s_waitcnt lgkmcnt(3)
	v_fmac_f32_e32 v50, v15, v30
	v_fmac_f32_e32 v50, v16, v31
	ds_read2_b32 v[38:39], v10 offset0:115 offset1:148
	s_waitcnt lgkmcnt(3)
	v_fmac_f32_e32 v50, v17, v34
	ds_read_b128 v[6:9], v1 offset:8912
	s_waitcnt lgkmcnt(3)
	v_fmac_f32_e32 v50, v2, v35
	ds_read2_b32 v[40:41], v10 offset0:181 offset1:214
	s_waitcnt lgkmcnt(3)
	v_fmac_f32_e32 v50, v3, v36
	v_add_u32_e32 v2, 0x4e00, v0
	v_fmac_f32_e32 v50, v4, v37
	ds_read2_b32 v[42:43], v2 offset0:119 offset1:152
	s_waitcnt lgkmcnt(3)
	v_fmac_f32_e32 v50, v5, v38
	ds_read_b128 v[2:5], v1 offset:8928
	s_waitcnt lgkmcnt(3)
	v_fmac_f32_e32 v50, v6, v39
	s_waitcnt lgkmcnt(2)
	v_fmac_f32_e32 v50, v7, v40
	v_fmac_f32_e32 v50, v8, v41
	v_add_u32_e32 v10, 0x5000, v0
	s_waitcnt lgkmcnt(1)
	v_fmac_f32_e32 v50, v9, v42
	ds_read2_b32 v[44:45], v10 offset0:57 offset1:90
	ds_read2_b32 v[46:47], v10 offset0:123 offset1:156
	ds_read_b128 v[6:9], v1 offset:8944
	s_waitcnt lgkmcnt(3)
	v_fmac_f32_e32 v50, v2, v43
	ds_read2_b32 v[48:49], v10 offset0:189 offset1:222
	s_waitcnt lgkmcnt(3)
	v_fmac_f32_e32 v50, v3, v44
	v_fmac_f32_e32 v50, v4, v45
	s_waitcnt lgkmcnt(2)
	v_fmac_f32_e32 v50, v5, v46
	s_waitcnt lgkmcnt(1)
	v_fmac_f32_e32 v50, v6, v47
	s_waitcnt lgkmcnt(0)
	v_fmac_f32_e32 v50, v7, v48
	v_fmac_f32_e32 v50, v8, v49
	v_fmac_f32_e32 v50, v9, v32
	v_xor_b32_e32 v2, 0x80000000, v50
	v_add_u32_e32 v1, v1, v98
	ds_write_b32 v1, v2 offset:8704
	v_add_u32_e32 v21, s78, v54
	ds_read_b128 v[2:5], v21 offset:8832
	ds_read_b128 v[6:9], v21 offset:8848
	ds_read_b128 v[10:13], v21 offset:8864
	ds_read_b128 v[14:17], v21 offset:8880
	ds_read_b32 v1, v0 offset:17408
	ds_read_b32 v25, v0 offset:17936
	ds_read_b32 v29, v0 offset:18464
	ds_read_b32 v35, v0 offset:18992
	ds_read_b32 v39, v0 offset:19520
	ds_read_b32 v43, v0 offset:20048
	ds_read_b32 v47, v0 offset:20576
	ds_read_b32 v50, v0 offset:21104
	s_waitcnt lgkmcnt(7)
	v_fma_f32 v51, v2, v1, 0
	v_fmac_f32_e32 v51, v18, v3
	v_fmac_f32_e32 v51, v19, v4
	v_fmac_f32_e32 v51, v20, v5
	s_waitcnt lgkmcnt(6)
	v_fmac_f32_e32 v51, v6, v25
	v_fmac_f32_e32 v51, v22, v7
	v_fmac_f32_e32 v51, v23, v8
	v_fmac_f32_e32 v51, v24, v9
	s_waitcnt lgkmcnt(5)
	v_fmac_f32_e32 v51, v10, v29
	v_fmac_f32_e32 v51, v26, v11
	v_fmac_f32_e32 v51, v27, v12
	v_fmac_f32_e32 v51, v28, v13
	ds_read_b128 v[0:3], v21 offset:8896
	ds_read_b128 v[4:7], v21 offset:8912
	s_waitcnt lgkmcnt(6)
	v_fmac_f32_e32 v51, v14, v35
	v_fmac_f32_e32 v51, v30, v15
	v_fmac_f32_e32 v51, v31, v16
	v_fmac_f32_e32 v51, v34, v17
	s_waitcnt lgkmcnt(1)
	v_fmac_f32_e32 v51, v0, v39
	v_fmac_f32_e32 v51, v36, v1
	v_fmac_f32_e32 v51, v37, v2
	v_fmac_f32_e32 v51, v38, v3
	ds_read_b128 v[0:3], v21 offset:8928
	s_waitcnt lgkmcnt(1)
	v_fmac_f32_e32 v51, v4, v43
	v_fmac_f32_e32 v51, v40, v5
	v_fmac_f32_e32 v51, v41, v6
	v_fmac_f32_e32 v51, v42, v7
	ds_read_b128 v[4:7], v21 offset:8944
	s_waitcnt lgkmcnt(1)
	v_fmac_f32_e32 v51, v0, v47
	v_fmac_f32_e32 v51, v44, v1
	v_fmac_f32_e32 v51, v45, v2
	v_fmac_f32_e32 v51, v46, v3
	s_waitcnt lgkmcnt(0)
	v_fmac_f32_e32 v51, v4, v50
	v_fmac_f32_e32 v51, v48, v5
	v_fmac_f32_e32 v51, v49, v6
	v_fmac_f32_e32 v51, v32, v7
	v_xor_b32_e32 v0, 0x80000000, v51
	v_add_u32_e32 v1, v21, v98
	v_ashrrev_i32_e32 v6, 3, v82
	v_and_b32_e32 v7, 7, v82
	ds_write_b32 v1, v0 offset:8704
	v_mul_lo_u32 v0, v6, s4
	v_lshlrev_b32_e32 v1, 5, v7
	s_waitcnt lgkmcnt(0)
	s_barrier
	v_add3_u32 v3, s78, v0, v1
	ds_read_b96 v[0:2], v3
	ds_read2_b32 v[4:5], v3 offset0:3 offset1:4
	ds_read_b32 v8, v3 offset:28
	v_add_lshl_u32 v32, s26, v6, 6
	s_xor_b32 s39, s39, 1
	s_waitcnt lgkmcnt(2)
	v_cvt_pk_f16_f32 v1, v1, v2
	ds_read2_b32 v[2:3], v3 offset0:5 offset1:6
	v_cvt_f16_f32_e32 v0, v0
	s_waitcnt lgkmcnt(2)
	v_cvt_pk_f16_f32 v4, v4, v5
	s_waitcnt lgkmcnt(1)
	v_cvt_f16_f32_e32 v5, v8
	s_and_b64 vcc, exec, s[10:11]
	s_waitcnt lgkmcnt(0)
	v_cvt_pk_f16_f32 v3, v2, v3
	v_pack_b32_f16 v0, v0, v1
	v_alignbit_b32 v1, v4, v1, 16
	v_alignbit_b32 v2, v3, v4, 16
	v_alignbit_b32 v3, v5, v3, 16
	v_lshl_add_u64 v[4:5], v[32:33], 1, s[0:1]
	v_lshlrev_b32_e32 v32, 4, v7
	v_lshl_add_u64 v[4:5], v[4:5], 0, v[32:33]
	global_store_dwordx4 v[4:5], v[0:3], off
	s_waitcnt lgkmcnt(0)
	s_barrier
	s_cbranch_vccnz .LBB0_430
	.p2align	6

; #define LDS_BARRIER() do { asm volatile("s_waitcnt lgkmcnt(0)" ::: "memory"); __builtin_amdgcn_s_barrier(); asm volatile("" ::: "memory"); } while (0)
; __device__ __forceinline__ void phase_attn(const h16* Pda, h16* ob, float* lse, int pat, unsigned char* ldsb) {
;     ...
;             if (pat < 2 && g == 0) gst(lse + tok * 12 + h, lse_new);
;         }
;         }
;         LDS_BARRIER();
;         }
.LBB0_448:
	s_or_b64 exec, exec, s[18:19]
	s_waitcnt lgkmcnt(0)
	s_barrier
	s_and_b64 vcc, exec, s[76:77]
	s_mov_b32 s35, s3
	s_cbranch_vccnz .LBB0_525
	.p2align	6
